# P2.5 work queue: next ticket's atomic issued one item ahead (held in a spare VGPR) and the ticket broadcast through LDS with ds ops instead of flat accesses
# speedup vs baseline: 1.0161x; 1.0071x over previous
; DEV void phase25(const Params& p, const bool fuse) {
;     ...
;         for (int g = 0; g < 16; ++g) { const int jl = (g & 3) + 8 * (g >> 2) + 4 * hh; if (jl > l31) X[g] = 0.f; }
;       }
;       *(bf16x8*)(smem + (wave * 2 + 0) * 1024 + lane * 16) = cvt8<0>(X);
;       *(bf16x8*)(smem + (wave * 2 + 1) * 1024 + lane * 16) = cvt8<1>(X);
;     }
;     f32x16 o[2][2];
; #pragma unroll
;     for (int dt = 0; dt < 2; ++dt)
; #pragma unroll
;       for (int i2 = 0; i2 < 2; ++i2)
; #pragma unroll
;         for (int q = 0; q < 4; ++q) {
;           const size_t idx = ((((size_t)((b * 32 + c) * 4 + h) * 16 + (2 * wave + dt)) * 2 + i2) * 4 + q) * 64 + lane;
;           const f32x4 a = unpk4(__builtin_nontemporal_load((const u32x2*)op0 + idx));
;           for (int j = 0; j < 4; ++j) o[dt][i2][4 * q + j] = a[j];
;         }
;     bf16x8 vfr[2][4];
; #pragma unroll
;     for (int dt = 0; dt < 2; ++dt)
; #pragma unroll
;       for (int s4 = 0; s4 < 4; ++s4) vfr[dt][s4] = ld16(gvT + ((size_t)(b * 2048 + h * 512 + 64 * wave + 32 * dt + l31)) * 2048 + tok0 + 16 * s4 + 8 * hh);
;     __syncthreads();
;     {
;       const char* lx = smem + lane * 16;
;       const bf16x8 x00a = *(const bf16x8*)(lx), x00b = *(const bf16x8*)(lx + 1024), x01a = *(const bf16x8*)(lx + 2048), x01b = *(const bf16x8*)(lx + 3072),
;                    x11a = *(const bf16x8*)(lx + 4096), x11b = *(const bf16x8*)(lx + 5120);
; #pragma unroll
;       for (int dt = 0; dt < 2; ++dt) {
;         o[dt][0] = mfma32(vfr[dt][0], x00a, o[dt][0]); o[dt][0] = mfma32(vfr[dt][1], x00b, o[dt][0]);
;         o[dt][1] = mfma32(vfr[dt][0], x01a, o[dt][1]); o[dt][1] = mfma32(vfr[dt][1], x01b, o[dt][1]);
;         o[dt][1] = mfma32(vfr[dt][2], x11a, o[dt][1]); o[dt][1] = mfma32(vfr[dt][3], x11b, o[dt][1]);
;       }
;     }
; #pragma unroll
;     for (int i2 = 0; i2 < 2; ++i2) {
;       float ss = 0.f;
; #pragma unroll
;       for (int dt = 0; dt < 2; ++dt) for (int g = 0; g < 16; ++g) ss += o[dt][i2][g] * o[dt][i2][g];
;       ss += __shfl_xor(ss, 32);
;       if (hh == 0) atomicAdd(&ssL[32 * i2 + l31], ss);
;     }
;     __syncthreads();
;     {
;       char* lw = smem + wave * 16384;
; #pragma unroll
;       for (int dt = 0; dt < 2; ++dt)
; #pragma unroll
;         for (int i2 = 0; i2 < 2; ++i2)
; #pragma unroll
;           for (int q = 0; q < 4; ++q) {
.LBB0_1227:
	s_load_dword s86, s[84:85], 0x0
	s_waitcnt lgkmcnt(0)
	s_cmpk_lt_u32 s86, 0x100
	s_cbranch_scc1 .LBB0_1255
	v_mov_b32_e32 v1, v179
	v_readlane_b32 s66, v254, 16
	v_readfirstlane_b32 s12, v1
	s_ashr_i32 s13, s12, 6
	s_cmp_lt_i32 s13, 3
	s_cselect_b64 s[42:43], -1, 0
	s_cmp_eq_u32 s13, 2
	s_cselect_b64 s[6:7], -1, 0
	s_and_b64 s[8:9], s[6:7], exec
	s_cselect_b32 s14, 32, 0
	s_cmp_gt_u32 s12, 63
	s_cselect_b64 s[8:9], -1, 0
	s_and_b64 s[10:11], s[8:9], exec
	v_bfe_u32 v6, v1, 5, 1
	s_cselect_b32 s10, 32, 0
	s_xor_b64 s[6:7], s[8:9], s[6:7]
	s_lshl_b32 s9, s13, 14
	v_lshlrev_b32_e32 v8, 4, v1
	v_lshlrev_b32_e32 v7, 2, v6
	s_add_i32 s9, s9, 0
	v_and_b32_e32 v8, 0xf0, v8
	v_and_b32_e32 v5, 31, v1
	v_add_u32_e32 v31, s9, v8
	v_or_b32_e32 v8, 2, v7
	s_xor_b64 s[44:45], s[6:7], -1
	s_lshl_b32 s6, s13, 11
	s_lshl_b32 s8, s13, 1
	s_and_b32 s33, s12, 0xffffffc0
	v_cmp_gt_u32_e64 s[12:13], v8, v5
	v_or_b32_e32 v8, 3, v7
	v_or_b32_e32 v86, s14, v5
	v_cmp_gt_u32_e64 s[14:15], v8, v5
	v_or_b32_e32 v8, 8, v7
	v_cmp_gt_u32_e64 s[16:17], v8, v5
	v_or_b32_e32 v8, 9, v7
	v_cmp_gt_u32_e64 s[18:19], v8, v5
	v_or_b32_e32 v8, 10, v7
	v_cmp_gt_u32_e64 s[20:21], v8, v5
	v_or_b32_e32 v8, 11, v7
	v_cmp_gt_u32_e64 s[22:23], v8, v5
	v_or_b32_e32 v8, 16, v7
	v_cmp_gt_u32_e64 s[24:25], v8, v5
	v_or_b32_e32 v8, 17, v7
	v_cmp_gt_u32_e64 s[26:27], v8, v5
	v_or_b32_e32 v8, 18, v7
	v_cmp_gt_u32_e64 s[28:29], v8, v5
	v_or_b32_e32 v8, 19, v7
	v_and_b32_e32 v4, 63, v1
	v_or_b32_e32 v88, s10, v5
	v_cmp_gt_u32_e64 s[10:11], v7, v5
	v_cmp_gt_u32_e64 s[30:31], v8, v5
	v_or_b32_e32 v8, 24, v7
	s_add_i32 s87, s6, 0
	v_lshlrev_b32_e32 v176, 3, v4
	v_readlane_b32 s6, v253, 15
	v_writelane_b32 v252, s10, 2
	v_cmp_gt_u32_e64 s[34:35], v8, v5
	v_or_b32_e32 v8, 25, v7
	v_lshl_add_u64 v[2:3], s[62:63], 0, v[176:177]
	v_lshlrev_b32_e32 v176, 4, v6
	v_readlane_b32 s7, v253, 16
	v_writelane_b32 v252, s11, 3
	v_cmp_lt_u32_e64 s[10:11], v7, v5
	v_cmp_gt_u32_e64 s[36:37], v8, v5
	v_or_b32_e32 v8, 26, v7
	v_or_b32_e32 v7, 27, v7
	v_lshlrev_b32_e32 v89, 4, v4
	v_or_b32_e32 v91, s33, v5
	v_lshl_add_u64 v[84:85], s[6:7], 0, v[176:177]
	v_cmp_gt_u32_e64 s[6:7], 32, v4
	v_lshl_add_u32 v93, v5, 2, s66
	v_lshl_add_u32 v30, v5, 8, s9
	v_and_b32_e32 v4, 15, v1
	v_cmp_gt_u32_e64 s[38:39], v8, v5
	v_cmp_gt_u32_e64 s[40:41], v7, v5
	v_bitop3_b32 v5, v6, v1, 15 bitop3:0x78
	v_lshlrev_b32_e32 v32, 4, v5
	v_bitop3_b32 v5, v6, v4, 2 bitop3:0x36
	v_lshlrev_b32_e32 v33, 4, v5
	v_bitop3_b32 v5, v6, v4, 4 bitop3:0x36
	v_lshlrev_b32_e32 v34, 4, v5
	v_bitop3_b32 v5, v6, v4, 6 bitop3:0x36
	v_lshlrev_b32_e32 v35, 4, v5
	v_bitop3_b32 v5, v6, v4, 8 bitop3:0x36
	v_lshlrev_b32_e32 v36, 4, v5
	v_bitop3_b32 v5, v6, v4, 10 bitop3:0x36
	v_lshlrev_b32_e32 v37, 4, v5
	v_bitop3_b32 v5, v6, v4, 12 bitop3:0x36
	v_bitop3_b32 v4, v6, v4, 14 bitop3:0x36
	v_bfe_u32 v90, v1, 4, 2
	v_cmp_eq_u32_e64 s[0:1], 0, v1
	v_cmp_gt_i32_e64 s[4:5], 64, v1
	v_lshl_add_u32 v87, v1, 2, s66
	v_lshlrev_b32_e32 v0, 3, v6
	v_lshlrev_b32_e32 v39, 4, v4
	v_xor_b32_e32 v4, v90, v1
	v_bitop3_b32 v6, v90, v1, 4 bitop3:0x36
	v_bitop3_b32 v8, v90, v1, 8 bitop3:0x36
	v_bitop3_b32 v10, v90, v1, 12 bitop3:0x36
	v_bitop3_b32 v12, v90, v1, 20 bitop3:0x36
	v_bitop3_b32 v14, v90, v1, 24 bitop3:0x36
	v_bitop3_b32 v16, v90, v1, 28 bitop3:0x36
	v_bitop3_b32 v18, v90, v1, 36 bitop3:0x36
	v_bitop3_b32 v20, v90, v1, 40 bitop3:0x36
	v_bitop3_b32 v22, v90, v1, 44 bitop3:0x36
	v_bitop3_b32 v24, v90, v1, 52 bitop3:0x36
	v_bitop3_b32 v26, v90, v1, 56 bitop3:0x36
	v_bitop3_b32 v1, v90, v1, 60 bitop3:0x36
	s_ashr_i32 s9, s8, 31
	s_or_b32 s64, s8, 1
	v_lshlrev_b32_e32 v4, 2, v4
	v_lshlrev_b32_e32 v6, 2, v6
	v_lshlrev_b32_e32 v8, 2, v8
	v_lshlrev_b32_e32 v10, 2, v10
	v_lshlrev_b32_e32 v12, 2, v12
	v_lshlrev_b32_e32 v14, 2, v14
	v_lshlrev_b32_e32 v16, 2, v16
	v_lshlrev_b32_e32 v18, 2, v18
	v_lshlrev_b32_e32 v20, 2, v20
	v_lshlrev_b32_e32 v22, 2, v22
	v_lshlrev_b32_e32 v24, 2, v24
	v_lshlrev_b32_e32 v26, 2, v26
	v_lshlrev_b32_e32 v1, 2, v1
	s_ashr_i32 s65, s64, 31
	v_and_or_b32 v4, v4, 60, s33
	v_or_b32_e32 v92, 4, v90
	v_and_or_b32 v6, v6, 60, s33
	v_or_b32_e32 v94, 8, v90
	v_and_or_b32 v8, v8, 60, s33
	v_or_b32_e32 v96, 12, v90
	v_and_or_b32 v10, v10, 60, s33
; DEV u32x2 pk4(f32x4 v) { u32x2 r = {pk_bf16(v[0], v[1]), pk_bf16(v[2], v[3])}; return r; }
; DEV f32x4 unpk4(u32x2 u) { f32x4 r = {bf_lo(u[0]), bf_hi(u[0]), bf_lo(u[1]), bf_hi(u[1])}; return r; }
; DEV void phase25(const Params& p, const bool fuse) {
;     ...
;             *(f32x4*)(lw + r * 256 + (((8 * dt + 2 * q + hh) ^ (r & 15)) * 16)) = v;
;           }
;       asm volatile("s_waitcnt lgkmcnt(0)" ::: "memory");
;       u32x2 sgv[16]; f32x4 ghv[16];
; #pragma unroll
;       for (int i = 0; i < 16; ++i) {
;         const int id = i * 64 + lane, r = id >> 4, pos = id & 15, c = pos ^ (r & 15);
;         const int dv = 64 * wave + 4 * c;
;         sgv[i] = __builtin_nontemporal_load((const u32x2*)(sgg + (grow + r) * 2048 + h * 512 + dv));
;         ghv[i] = *(const f32x4*)(p.g_head + dv);
;       }
; #pragma unroll
;       for (int i = 0; i < 16; ++i) {
;         const int id = i * 64 + lane, r = id >> 4, pos = id & 15, c = pos ^ (r & 15);
;         const f32x4 v = *(const f32x4*)(lw + r * 256 + pos * 16);
;         const float rstd = rsqrtf(ssL[r] * (1.f / 512.f) + 1e-6f);
;         const int dv = 64 * wave + 4 * c;
;         *(u32x2*)(oa + (grow + r) * 2048 + h * 512 + dv) = pk4(v * rstd * ghv[i] * unpk4(sgv[i]));
	v_or_b32_e32 v98, 16, v90
	v_or_b32_e32 v100, 20, v90
	v_and_or_b32 v12, v12, 60, s33
	v_or_b32_e32 v102, 24, v90
	v_and_or_b32 v14, v14, 60, s33
	v_or_b32_e32 v104, 28, v90
	v_and_or_b32 v16, v16, 60, s33
	v_or_b32_e32 v106, 32, v90
	v_or_b32_e32 v108, 36, v90
	v_and_or_b32 v18, v18, 60, s33
	v_or_b32_e32 v110, 40, v90
	v_and_or_b32 v20, v20, 60, s33
	v_or_b32_e32 v112, 44, v90
	v_and_or_b32 v22, v22, 60, s33
	v_or_b32_e32 v114, 48, v90
	v_or_b32_e32 v116, 52, v90
	v_and_or_b32 v24, v24, 60, s33
	v_or_b32_e32 v118, 56, v90
	v_and_or_b32 v26, v26, 60, s33
	v_or_b32_e32 v120, 60, v90
	v_and_or_b32 v28, v1, 60, s33
	s_lshl_b64 s[8:9], s[8:9], 12
	v_lshlrev_b32_e32 v38, 4, v5
	v_ashrrev_i32_e32 v5, 31, v4
	v_ashrrev_i32_e32 v7, 31, v6
	v_ashrrev_i32_e32 v9, 31, v8
	v_ashrrev_i32_e32 v11, 31, v10
	v_ashrrev_i32_e32 v13, 31, v12
	v_ashrrev_i32_e32 v15, 31, v14
	v_ashrrev_i32_e32 v17, 31, v16
	v_ashrrev_i32_e32 v19, 31, v18
	v_ashrrev_i32_e32 v21, 31, v20
	v_ashrrev_i32_e32 v23, 31, v22
	v_ashrrev_i32_e32 v25, 31, v24
	v_ashrrev_i32_e32 v27, 31, v26
	v_ashrrev_i32_e32 v29, 31, v28
	v_lshlrev_b32_e32 v1, 8, v90
	v_lshlrev_b32_e32 v40, 8, v92
	v_lshlrev_b32_e32 v41, 8, v94
	v_lshlrev_b32_e32 v42, 8, v96
	v_lshlrev_b32_e32 v43, 8, v98
	v_lshlrev_b32_e32 v44, 8, v100
	v_lshlrev_b32_e32 v45, 8, v102
	v_lshlrev_b32_e32 v46, 8, v104
	v_lshlrev_b32_e32 v47, 8, v106
	v_lshlrev_b32_e32 v48, 8, v108
	v_lshlrev_b32_e32 v49, 8, v110
	v_lshlrev_b32_e32 v50, 8, v112
	v_lshlrev_b32_e32 v51, 8, v114
	v_lshlrev_b32_e32 v52, 8, v116
	v_lshlrev_b32_e32 v53, 8, v118
	v_lshlrev_b32_e32 v54, 8, v120
	v_lshl_add_u64 v[122:123], v[2:3], 0, s[8:9]
	s_lshl_b64 s[8:9], s[64:65], 12
	v_lshl_add_u32 v95, v90, 2, s66
	v_lshl_add_u32 v97, v92, 2, s66
	v_lshl_add_u32 v99, v94, 2, s66
	v_lshl_add_u32 v101, v96, 2, s66
	v_lshl_add_u32 v103, v98, 2, s66
	v_lshl_add_u32 v105, v100, 2, s66
	v_lshl_add_u32 v107, v102, 2, s66
	v_lshl_add_u32 v109, v104, 2, s66
	v_lshl_add_u32 v111, v106, 2, s66
	v_lshl_add_u32 v113, v108, 2, s66
	v_lshl_add_u32 v115, v110, 2, s66
	v_lshl_add_u32 v117, v112, 2, s66
	v_lshl_add_u32 v119, v114, 2, s66
	v_lshl_add_u32 v121, v116, 2, s66
	v_lshl_add_u32 v212, v118, 2, s66
	v_lshl_add_u32 v213, v120, 2, s66
	v_lshl_add_u64 v[124:125], v[2:3], 0, s[8:9]
	v_lshl_add_u64 v[126:127], v[4:5], 2, s[48:49]
	v_lshl_add_u64 v[128:129], v[6:7], 2, s[48:49]
	v_lshl_add_u64 v[130:131], v[8:9], 2, s[48:49]
	v_lshl_add_u64 v[132:133], v[10:11], 2, s[48:49]
	v_lshl_add_u64 v[134:135], v[12:13], 2, s[48:49]
	v_lshl_add_u64 v[136:137], v[14:15], 2, s[48:49]
	v_lshl_add_u64 v[138:139], v[16:17], 2, s[48:49]
	v_lshl_add_u64 v[140:141], v[18:19], 2, s[48:49]
	v_lshl_add_u64 v[142:143], v[20:21], 2, s[48:49]
	v_lshl_add_u64 v[144:145], v[22:23], 2, s[48:49]
	v_lshl_add_u64 v[146:147], v[24:25], 2, s[48:49]
	v_lshl_add_u64 v[148:149], v[26:27], 2, s[48:49]
	v_lshl_add_u64 v[150:151], v[28:29], 2, s[48:49]
	v_lshlrev_b32_e32 v176, 1, v0
	v_add_u32_e32 v214, v30, v32
	v_add_u32_e32 v215, v30, v33
	v_add_u32_e32 v216, v30, v34
	v_add_u32_e32 v217, v30, v35
	v_add_u32_e32 v223, v30, v36
	v_add_u32_e32 v224, v30, v37
	v_add_u32_e32 v225, v30, v38
	v_add_u32_e32 v226, v30, v39
	v_lshlrev_b64 v[152:153], 1, v[4:5]
	v_lshlrev_b64 v[154:155], 1, v[6:7]
	v_lshlrev_b64 v[156:157], 1, v[8:9]
	v_lshlrev_b64 v[158:159], 1, v[10:11]
	v_lshlrev_b64 v[160:161], 1, v[12:13]
	v_lshlrev_b64 v[162:163], 1, v[14:15]
	v_lshlrev_b64 v[164:165], 1, v[16:17]
	v_lshlrev_b64 v[166:167], 1, v[18:19]
	v_lshlrev_b64 v[168:169], 1, v[20:21]
	v_lshlrev_b64 v[170:171], 1, v[22:23]
	v_lshlrev_b64 v[172:173], 1, v[24:25]
	v_lshlrev_b64 v[174:175], 1, v[26:27]
	v_lshlrev_b64 v[180:181], 1, v[28:29]
	v_add_u32_e32 v227, v31, v1
	v_add_u32_e32 v228, v31, v40
	v_add_u32_e32 v229, v31, v41
	v_add_u32_e32 v230, v31, v42
	v_add_u32_e32 v231, v31, v43
	v_add_u32_e32 v232, v31, v44
	v_add_u32_e32 v233, v31, v45
	v_add_u32_e32 v234, v31, v46
	v_add_u32_e32 v235, v31, v47
	v_add_u32_e32 v236, v31, v48
	v_add_u32_e32 v237, v31, v49
	v_add_u32_e32 v238, v31, v50
	v_add_u32_e32 v239, v31, v51
	v_add_u32_e32 v240, v31, v52
	v_add_u32_e32 v241, v31, v53
	v_add_u32_e32 v242, v31, v54
	s_mov_b32 s3, 0
	s_branch .LBB0_1232

; DEV void panel_wait(unsigned* cnt, const unsigned need, const int tidx) {
;   if (tidx == 0) {
;     while (__hip_atomic_load(cnt, __ATOMIC_RELAXED, __HIP_MEMORY_SCOPE_AGENT) < need) __builtin_amdgcn_s_sleep(2);
; DEV void phase25(const Params& p, const bool fuse) {
;     ...
;     if (fuse) {
;       __syncthreads();
;       if (tidx == 0) *slot25 = (int)atomicAdd(ctr25, 1u);
;       __syncthreads();
;       it = __builtin_amdgcn_readfirstlane(*slot25);
;     } else { it = itn; itn += gridDim.x; }
;     if (it >= 512) break;
;     const int bh = it >> 5, c = it & 31, b = bh >> 2, h = bh & 3, tok0 = c * 64;
;     const size_t grow = (size_t)b * 2048 + tok0;
;     if (fuse) panel_wait((unsigned*)(p.ws + OFF_MISC + 2048 + 768) + bh, 4u, tidx);
.LBB0_1232:
	s_barrier
	s_and_saveexec_b64 s[8:9], s[0:1]
	s_cbranch_execz .LBB0_1236
	s_mov_b64 s[66:67], exec
	v_mbcnt_lo_u32_b32 v0, s66, 0
	v_mbcnt_hi_u32_b32 v0, s67, v0
	v_cmp_eq_u32_e32 vcc, 0, v0
	s_and_saveexec_b64 s[64:65], vcc
	s_cbranch_execz .LBB0_1235
	v_readlane_b32 s66, v253, 60
	v_readlane_b32 s67, v253, 61
	s_cmp_eq_u32 s3, 0
	s_cbranch_scc0 .Lq25_have
	v_mov_b32_e32 v250, 1
	s_nop 4
	global_atomic_add v250, v177, v250, s[66:67] sc0
	s_mov_b32 s3, 1
.Lq25_have:
	s_waitcnt vmcnt(0)
	v_mov_b32_e32 v1, v250
	v_mov_b32_e32 v250, 1
	s_nop 4
	global_atomic_add v250, v177, v250, s[66:67] sc0
.LBB0_1235:
	s_or_b64 exec, exec, s[64:65]
	s_nop 0
	s_nop 0
	v_readfirstlane_b32 s33, v1
	s_nop 0
	v_add_u32_e32 v2, s33, v0
	v_mov_b32_e32 v0, s71
	ds_write_b32 v0, v2
	s_waitcnt lgkmcnt(0)
.LBB0_1236:
	s_or_b64 exec, exec, s[8:9]
	v_mov_b32_e32 v0, s71
	s_waitcnt lgkmcnt(0)
	s_barrier
	ds_read_b32 v0, v0
	s_mov_b64 s[8:9], -1
	s_waitcnt lgkmcnt(0)
	v_readfirstlane_b32 s69, v0
	s_cmpk_gt_i32 s69, 0x1ff
	s_cbranch_scc1 .LBB0_1231
	s_ashr_i32 s64, s69, 5
	s_and_saveexec_b64 s[8:9], s[0:1]
	s_cbranch_execz .LBB0_1241
	s_ashr_i32 s65, s64, 31
	s_lshl_b64 s[66:67], s[64:65], 2
	v_readlane_b32 s33, v253, 29
	s_add_u32 s66, s33, s66
	v_readlane_b32 s33, v253, 30
	s_addc_u32 s67, s33, s67
	global_load_dword v0, v177, s[66:67] sc1
	s_waitcnt vmcnt(0)
	v_cmp_lt_u32_e32 vcc, 3, v0
	s_cbranch_vccnz .LBB0_1240
